# EpiUp act stores also lane-transposed via ds_bpermute (coalesced 64B per 4 lanes), on top of proj
# baseline (speedup 1.0000x reference)
.LBB0_408:
	s_or_b64 exec, exec, s[38:39]
	s_mov_b32 s4, 0x358637bd
	v_pk_add_f32 v[240:241], v[240:241], v[242:243]
	v_mov_b64_e32 v[214:215], s[4:5]
	v_pk_fma_f32 v[240:241], v[240:241], s[90:91], v[214:215] op_sel_hi:[1,0,0]
	v_pk_add_f32 v[236:237], v[236:237], v[238:239]
	v_mul_f32_e32 v216, 0x4b800000, v240
	v_cmp_gt_f32_e64 s[42:43], s10, v240
	v_cmp_gt_f32_e32 vcc, s10, v241
	v_pk_fma_f32 v[214:215], v[236:237], s[90:91], v[214:215] op_sel_hi:[1,0,0]
	v_cndmask_b32_e64 v216, v240, v216, s[42:43]
	v_rsq_f32_e32 v216, v216
	s_mov_b64 s[26:27], -1
	v_mul_f32_e32 v217, 0x45800000, v216
	v_cndmask_b32_e64 v240, v216, v217, s[42:43]
	v_mul_f32_e32 v216, 0x4b800000, v241
	v_cndmask_b32_e32 v216, v241, v216, vcc
	v_rsq_f32_e32 v216, v216
	v_cmp_gt_f32_e64 s[42:43], s10, v214
	v_pk_mul_f32 v[16:17], v[16:17], v[240:241] op_sel_hi:[1,0]
	v_mul_f32_e32 v217, 0x45800000, v216
	v_cndmask_b32_e32 v242, v216, v217, vcc
	v_mul_f32_e32 v216, 0x4b800000, v214
	v_cndmask_b32_e64 v214, v214, v216, s[42:43]
	v_rsq_f32_e32 v214, v214
	v_cmp_gt_f32_e32 vcc, s10, v215
	v_pk_mul_f32 v[220:221], v[68:69], v[242:243] op_sel_hi:[1,0]
	v_pk_mul_f32 v[218:219], v[66:67], v[242:243] op_sel_hi:[1,0]
	v_mul_f32_e32 v216, 0x45800000, v214
	v_cndmask_b32_e64 v236, v214, v216, s[42:43]
	v_mul_f32_e32 v214, 0x4b800000, v215
	v_cndmask_b32_e32 v214, v215, v214, vcc
	v_rsq_f32_e32 v214, v214
	v_pk_mul_f32 v[216:217], v[72:73], v[240:241] op_sel_hi:[1,0]
	v_pk_mul_f32 v[72:73], v[64:65], v[236:237] op_sel_hi:[1,0]
	s_waitcnt vmcnt(3)
	v_pk_mul_f32 v[64:65], v[154:155], v[198:199]
	v_mul_f32_e32 v215, 0x45800000, v214
	v_cndmask_b32_e32 v238, v214, v215, vcc
	v_pk_mul_f32 v[68:69], v[60:61], v[238:239] op_sel_hi:[1,0]
	v_pk_mul_f32 v[60:61], v[178:179], v[198:199]
	v_pk_mul_f32 v[66:67], v[58:59], v[238:239] op_sel_hi:[1,0]
	v_pk_mul_f32 v[58:59], v[180:181], v[200:201]
	v_pk_fma_f32 v[60:61], v[154:155], v[194:195], v[60:61]
	v_pk_mul_f32 v[214:215], v[70:71], v[240:241] op_sel_hi:[1,0]
	v_pk_mul_f32 v[70:71], v[62:63], v[236:237] op_sel_hi:[1,0]
	v_pk_fma_f32 v[58:59], v[156:157], v[196:197], v[58:59]
	v_pk_fma_f32 v[60:61], v[66:67], v[190:191], v[60:61]
	v_pk_mul_f32 v[62:63], v[156:157], v[200:201]
	v_pk_fma_f32 v[64:65], v[66:67], v[194:195], v[64:65]
	v_pk_mul_f32 v[66:67], v[66:67], v[198:199]
	v_pk_fma_f32 v[58:59], v[68:69], v[192:193], v[58:59]
	v_pk_fma_f32 v[62:63], v[68:69], v[196:197], v[62:63]
	v_pk_fma_f32 v[64:65], v[70:71], v[190:191], v[64:65]
	v_pk_mul_f32 v[68:69], v[68:69], v[200:201]
	v_pk_fma_f32 v[154:155], v[70:71], v[194:195], v[66:67]
	v_pk_mul_f32 v[70:71], v[70:71], v[198:199]
	v_pk_fma_f32 v[62:63], v[72:73], v[192:193], v[62:63]
	v_pk_fma_f32 v[66:67], v[72:73], v[196:197], v[68:69]
	v_pk_fma_f32 v[68:69], v[218:219], v[190:191], v[154:155]
	v_pk_mul_f32 v[72:73], v[72:73], v[200:201]
	v_pk_fma_f32 v[154:155], v[218:219], v[194:195], v[70:71]
	v_pk_fma_f32 v[70:71], v[220:221], v[196:197], v[72:73]
	v_pk_fma_f32 v[72:73], v[214:215], v[190:191], v[154:155]
	v_pk_mul_f32 v[154:155], v[220:221], v[200:201]
	v_pk_mul_f32 v[156:157], v[218:219], v[198:199]
	v_pk_fma_f32 v[154:155], v[216:217], v[196:197], v[154:155]
	v_pk_fma_f32 v[156:157], v[214:215], v[194:195], v[156:157]
	v_pk_mul_f32 v[178:179], v[216:217], v[200:201]
	v_pk_mul_f32 v[180:181], v[214:215], v[198:199]
	v_pk_fma_f32 v[154:155], v[128:129], v[192:193], v[154:155]
	v_pk_fma_f32 v[156:157], v[126:127], v[190:191], v[156:157]
	v_pk_fma_f32 v[180:181], v[126:127], v[194:195], v[180:181]
	v_pk_fma_f32 v[178:179], v[128:129], v[196:197], v[178:179]
	v_pk_mul_f32 v[128:129], v[128:129], v[200:201]
	v_pk_mul_f32 v[126:127], v[126:127], v[198:199]
	v_pk_fma_f32 v[128:129], v[124:125], v[196:197], v[128:129]
	v_pk_fma_f32 v[214:215], v[122:123], v[194:195], v[126:127]
	s_waitcnt lgkmcnt(0)
	v_pk_mul_f32 v[196:197], v[196:197], v[204:205]
	v_pk_mul_f32 v[194:195], v[194:195], v[202:203]
	v_pk_fma_f32 v[178:179], v[124:125], v[192:193], v[178:179]
	v_pk_fma_f32 v[124:125], v[124:125], v[200:201], v[196:197]
	v_pk_fma_f32 v[194:195], v[122:123], v[198:199], v[194:195]
	v_pk_mul_f32 v[198:199], v[38:39], v[236:237] op_sel_hi:[1,0]
	v_pk_mul_f32 v[200:201], v[40:41], v[236:237] op_sel_hi:[1,0]
	v_pk_mul_f32 v[38:39], v[144:145], v[176:177]
	v_pk_mul_f32 v[40:41], v[142:143], v[174:175]
	v_pk_mul_f32 v[34:35], v[34:35], v[238:239] op_sel_hi:[1,0]
	v_pk_mul_f32 v[36:37], v[36:37], v[238:239] op_sel_hi:[1,0]
	v_pk_fma_f32 v[38:39], v[136:137], v[164:165], v[38:39]
	v_pk_fma_f32 v[40:41], v[134:135], v[162:163], v[40:41]
	v_pk_fma_f32 v[66:67], v[220:221], v[192:193], v[66:67]
	v_pk_fma_f32 v[70:71], v[216:217], v[192:193], v[70:71]
	v_pk_fma_f32 v[180:181], v[122:123], v[190:191], v[180:181]
	v_pk_fma_f32 v[126:127], v[192:193], v[204:205], v[128:129]
	v_pk_fma_f32 v[128:129], v[190:191], v[202:203], v[214:215]
	v_pk_fma_f32 v[122:123], v[192:193], v[208:209], v[124:125]
	v_pk_fma_f32 v[124:125], v[190:191], v[206:207], v[194:195]
	v_pk_mul_f32 v[190:191], v[54:55], v[240:241] op_sel_hi:[1,0]
	v_pk_mul_f32 v[192:193], v[56:57], v[240:241] op_sel_hi:[1,0]
	v_pk_fma_f32 v[56:57], v[36:37], v[160:161], v[38:39]
	v_pk_fma_f32 v[54:55], v[34:35], v[158:159], v[40:41]
	v_pk_mul_f32 v[38:39], v[136:137], v[176:177]
	v_pk_mul_f32 v[40:41], v[134:135], v[174:175]
	v_pk_fma_f32 v[38:39], v[36:37], v[164:165], v[38:39]
	v_pk_fma_f32 v[40:41], v[34:35], v[162:163], v[40:41]
	v_pk_mul_f32 v[36:37], v[36:37], v[176:177]
	v_pk_mul_f32 v[34:35], v[34:35], v[174:175]
	v_pk_mul_f32 v[194:195], v[50:51], v[242:243] op_sel_hi:[1,0]
	v_pk_mul_f32 v[196:197], v[52:53], v[242:243] op_sel_hi:[1,0]
	v_pk_fma_f32 v[34:35], v[198:199], v[162:163], v[34:35]
	v_pk_fma_f32 v[36:37], v[200:201], v[164:165], v[36:37]
	v_pk_fma_f32 v[52:53], v[200:201], v[160:161], v[38:39]
	v_pk_fma_f32 v[50:51], v[198:199], v[158:159], v[40:41]
	v_pk_fma_f32 v[40:41], v[196:197], v[160:161], v[36:37]
	v_pk_fma_f32 v[38:39], v[194:195], v[158:159], v[34:35]
	v_pk_mul_f32 v[34:35], v[200:201], v[176:177]
	v_pk_mul_f32 v[36:37], v[198:199], v[174:175]
	v_pk_fma_f32 v[34:35], v[196:197], v[164:165], v[34:35]
	v_pk_fma_f32 v[134:135], v[194:195], v[162:163], v[36:37]
	v_pk_mul_f32 v[136:137], v[194:195], v[174:175]
	v_pk_fma_f32 v[36:37], v[192:193], v[160:161], v[34:35]
	v_pk_fma_f32 v[34:35], v[190:191], v[158:159], v[134:135]
	v_pk_mul_f32 v[134:135], v[196:197], v[176:177]
	v_pk_fma_f32 v[136:137], v[190:191], v[162:163], v[136:137]
	v_pk_mul_f32 v[144:145], v[190:191], v[174:175]
	v_pk_fma_f32 v[134:135], v[192:193], v[164:165], v[134:135]
	v_pk_fma_f32 v[136:137], v[118:119], v[158:159], v[136:137]
	v_pk_mul_f32 v[142:143], v[192:193], v[176:177]
	v_pk_fma_f32 v[144:145], v[118:119], v[162:163], v[144:145]
	v_pk_mul_f32 v[118:119], v[118:119], v[174:175]
	v_pk_fma_f32 v[134:135], v[120:121], v[160:161], v[134:135]
	v_pk_fma_f32 v[142:143], v[120:121], v[164:165], v[142:143]
	v_pk_mul_f32 v[120:121], v[120:121], v[176:177]
	v_pk_fma_f32 v[118:119], v[114:115], v[162:163], v[118:119]
	v_pk_fma_f32 v[120:121], v[116:117], v[164:165], v[120:121]
	v_pk_fma_f32 v[192:193], v[158:159], v[182:183], v[118:119]
	v_pk_mul_f32 v[118:119], v[164:165], v[184:185]
	v_pk_mul_f32 v[164:165], v[30:31], v[240:241] op_sel_hi:[1,0]
	v_pk_mul_f32 v[30:31], v[132:133], v[152:153]
	v_pk_fma_f32 v[142:143], v[116:117], v[160:161], v[142:143]
	v_pk_fma_f32 v[116:117], v[116:117], v[176:177], v[118:119]
	v_pk_mul_f32 v[20:21], v[20:21], v[238:239] op_sel_hi:[1,0]
	v_pk_fma_f32 v[30:31], v[104:105], v[148:149], v[30:31]
	v_pk_fma_f32 v[190:191], v[160:161], v[184:185], v[120:121]
	v_pk_fma_f32 v[160:161], v[160:161], v[188:189], v[116:117]
	v_pk_fma_f32 v[116:117], v[20:21], v[140:141], v[30:31]
	v_pk_mul_f32 v[30:31], v[104:105], v[152:153]
	v_pk_mul_f32 v[120:121], v[162:163], v[182:183]
	v_pk_mul_f32 v[162:163], v[32:33], v[240:241] op_sel_hi:[1,0]
	v_pk_mul_f32 v[24:25], v[24:25], v[236:237] op_sel_hi:[1,0]
	v_pk_mul_f32 v[32:33], v[130:131], v[150:151]
	v_pk_fma_f32 v[30:31], v[20:21], v[148:149], v[30:31]
	v_pk_mul_f32 v[20:21], v[20:21], v[152:153]
	v_pk_fma_f32 v[144:145], v[114:115], v[158:159], v[144:145]
	v_pk_fma_f32 v[114:115], v[114:115], v[174:175], v[120:121]
	v_pk_mul_f32 v[28:29], v[28:29], v[242:243] op_sel_hi:[1,0]
	v_pk_mul_f32 v[18:19], v[18:19], v[238:239] op_sel_hi:[1,0]
	v_pk_fma_f32 v[32:33], v[102:103], v[146:147], v[32:33]
	v_pk_fma_f32 v[20:21], v[24:25], v[148:149], v[20:21]
	v_pk_fma_f32 v[158:159], v[158:159], v[186:187], v[114:115]
	v_pk_fma_f32 v[114:115], v[18:19], v[138:139], v[32:33]
	v_pk_mul_f32 v[32:33], v[102:103], v[150:151]
	v_pk_fma_f32 v[120:121], v[28:29], v[140:141], v[20:21]
	v_pk_mul_f32 v[20:21], v[24:25], v[152:153]
	v_pk_mul_f32 v[22:23], v[22:23], v[236:237] op_sel_hi:[1,0]
	v_pk_fma_f32 v[32:33], v[18:19], v[146:147], v[32:33]
	v_pk_mul_f32 v[18:19], v[18:19], v[150:151]
	v_pk_fma_f32 v[20:21], v[28:29], v[148:149], v[20:21]
	v_pk_mul_f32 v[26:27], v[26:27], v[242:243] op_sel_hi:[1,0]
	v_pk_fma_f32 v[18:19], v[22:23], v[146:147], v[18:19]
	v_pk_fma_f32 v[132:133], v[162:163], v[140:141], v[20:21]
	v_pk_mul_f32 v[20:21], v[28:29], v[152:153]
	v_pk_fma_f32 v[118:119], v[26:27], v[138:139], v[18:19]
	v_pk_mul_f32 v[18:19], v[22:23], v[150:151]
	v_pk_fma_f32 v[20:21], v[162:163], v[148:149], v[20:21]
	v_pk_fma_f32 v[102:103], v[22:23], v[138:139], v[32:33]
	v_pk_fma_f32 v[18:19], v[26:27], v[146:147], v[18:19]
	v_pk_fma_f32 v[32:33], v[112:113], v[140:141], v[20:21]
	v_pk_mul_f32 v[20:21], v[162:163], v[152:153]
	v_pk_fma_f32 v[130:131], v[164:165], v[138:139], v[18:19]
	v_pk_mul_f32 v[18:19], v[26:27], v[150:151]
	v_pk_fma_f32 v[20:21], v[112:113], v[148:149], v[20:21]
	v_pk_fma_f32 v[18:19], v[164:165], v[146:147], v[18:19]
	v_pk_fma_f32 v[28:29], v[108:109], v[140:141], v[20:21]
	v_pk_mul_f32 v[20:21], v[110:111], v[150:151]
	v_pk_fma_f32 v[104:105], v[24:25], v[140:141], v[30:31]
	v_pk_fma_f32 v[30:31], v[110:111], v[138:139], v[18:19]
	v_pk_mul_f32 v[18:19], v[164:165], v[150:151]
	v_pk_fma_f32 v[20:21], v[106:107], v[146:147], v[20:21]
	v_pk_fma_f32 v[18:19], v[110:111], v[146:147], v[18:19]
	v_pk_fma_f32 v[24:25], v[138:139], v[166:167], v[20:21]
	v_pk_mul_f32 v[20:21], v[146:147], v[166:167]
	v_pk_fma_f32 v[26:27], v[106:107], v[138:139], v[18:19]
	v_pk_fma_f32 v[20:21], v[106:107], v[150:151], v[20:21]
	v_mul_f32_e32 v106, 0xbfb8aa3b, v158
	v_mul_f32_e32 v107, 0xbfb8aa3b, v159
	v_exp_f32_e32 v106, v106
	v_exp_f32_e32 v107, v107
	v_pk_mul_f32 v[18:19], v[112:113], v[152:153]
	v_pk_fma_f32 v[20:21], v[138:139], v[170:171], v[20:21]
	v_pk_fma_f32 v[18:19], v[108:109], v[148:149], v[18:19]
	v_add_f32_e32 v106, 1.0, v106
	v_add_f32_e32 v107, 1.0, v107
	v_pk_fma_f32 v[22:23], v[140:141], v[168:169], v[18:19]
	v_pk_mul_f32 v[18:19], v[148:149], v[168:169]
	v_rcp_f32_e32 v106, v106
	v_rcp_f32_e32 v107, v107
	v_pk_fma_f32 v[18:19], v[108:109], v[152:153], v[18:19]
	v_pk_mul_f32 v[26:27], v[144:145], v[26:27]
	v_pk_fma_f32 v[18:19], v[140:141], v[172:173], v[18:19]
	v_pk_mul_f32 v[28:29], v[142:143], v[28:29]
	v_pk_mul_f32 v[108:109], v[160:161], v[18:19]
	v_pk_mul_f32 v[18:19], v[158:159], v[20:21]
	v_mul_f32_e32 v20, 0xbfb8aa3b, v160
	v_mul_f32_e32 v21, 0xbfb8aa3b, v161
	v_pk_mul_f32 v[18:19], v[106:107], v[18:19]
	v_exp_f32_e32 v20, v20
	v_exp_f32_e32 v21, v21
	v_mul_f32_e32 v106, 0xbfb8aa3b, v192
	v_mul_f32_e32 v107, 0xbfb8aa3b, v193
	v_exp_f32_e32 v106, v106
	v_exp_f32_e32 v107, v107
	v_add_f32_e32 v20, 1.0, v20
	v_add_f32_e32 v21, 1.0, v21
	v_rcp_f32_e32 v20, v20
	v_rcp_f32_e32 v21, v21
	v_add_f32_e32 v106, 1.0, v106
	v_add_f32_e32 v107, 1.0, v107
	v_rcp_f32_e32 v106, v106
	v_rcp_f32_e32 v107, v107
	v_pk_mul_f32 v[20:21], v[20:21], v[108:109]
	v_pk_mul_f32 v[108:109], v[190:191], v[22:23]
	v_pk_mul_f32 v[22:23], v[192:193], v[24:25]
	v_pk_mul_f32 v[30:31], v[136:137], v[30:31]
	v_pk_mul_f32 v[22:23], v[106:107], v[22:23]
	v_mul_f32_e32 v106, 0xbfb8aa3b, v144
	v_mul_f32_e32 v107, 0xbfb8aa3b, v145
	v_exp_f32_e32 v106, v106
	v_exp_f32_e32 v107, v107
	v_mul_f32_e32 v24, 0xbfb8aa3b, v190
	v_mul_f32_e32 v25, 0xbfb8aa3b, v191
	v_add_f32_e32 v106, 1.0, v106
	v_add_f32_e32 v107, 1.0, v107
	v_rcp_f32_e32 v106, v106
	v_rcp_f32_e32 v107, v107
	v_pk_mul_f32 v[32:33], v[134:135], v[32:33]
	v_exp_f32_e32 v24, v24
	v_exp_f32_e32 v25, v25
	v_pk_mul_f32 v[26:27], v[106:107], v[26:27]
	v_mul_f32_e32 v106, 0xbfb8aa3b, v142
	v_mul_f32_e32 v107, 0xbfb8aa3b, v143
	v_exp_f32_e32 v106, v106
	v_exp_f32_e32 v107, v107
	v_add_f32_e32 v24, 1.0, v24
	v_add_f32_e32 v25, 1.0, v25
	v_add_f32_e32 v106, 1.0, v106
	v_add_f32_e32 v107, 1.0, v107
	v_rcp_f32_e32 v106, v106
	v_rcp_f32_e32 v107, v107
	v_rcp_f32_e32 v24, v24
	v_rcp_f32_e32 v25, v25
	v_pk_mul_f32 v[104:105], v[52:53], v[104:105]
	v_pk_mul_f32 v[28:29], v[106:107], v[28:29]
	v_mul_f32_e32 v106, 0xbfb8aa3b, v136
	v_mul_f32_e32 v107, 0xbfb8aa3b, v137
	v_exp_f32_e32 v106, v106
	v_exp_f32_e32 v107, v107
	v_pk_mul_f32 v[24:25], v[24:25], v[108:109]
	v_pk_mul_f32 v[108:109], v[36:37], v[132:133]
	v_add_f32_e32 v106, 1.0, v106
	v_add_f32_e32 v107, 1.0, v107
	v_rcp_f32_e32 v106, v106
	v_rcp_f32_e32 v107, v107
	v_mul_f32_e32 v36, 0xbfb8aa3b, v36
	v_mul_f32_e32 v37, 0xbfb8aa3b, v37
	v_exp_f32_e32 v36, v36
	v_pk_mul_f32 v[30:31], v[106:107], v[30:31]
	v_mul_f32_e32 v106, 0xbfb8aa3b, v134
	v_mul_f32_e32 v107, 0xbfb8aa3b, v135
	v_exp_f32_e32 v106, v106
	v_exp_f32_e32 v107, v107
	v_exp_f32_e32 v37, v37
	v_mul_f32_e32 v52, 0xbfb8aa3b, v52
	v_add_f32_e32 v106, 1.0, v106
	v_add_f32_e32 v107, 1.0, v107
	v_rcp_f32_e32 v106, v106
	v_rcp_f32_e32 v107, v107
	v_mul_f32_e32 v53, 0xbfb8aa3b, v53
	v_exp_f32_e32 v52, v52
	v_exp_f32_e32 v53, v53
	v_pk_mul_f32 v[32:33], v[106:107], v[32:33]
	v_mul_f32_e32 v106, 0xbfb8aa3b, v34
	v_mul_f32_e32 v107, 0xbfb8aa3b, v35
	v_exp_f32_e32 v106, v106
	v_exp_f32_e32 v107, v107
	v_pk_mul_f32 v[34:35], v[34:35], v[130:131]
	v_add_f32_e32 v36, 1.0, v36
	v_add_f32_e32 v106, 1.0, v106
	v_add_f32_e32 v107, 1.0, v107
	v_rcp_f32_e32 v106, v106
	v_rcp_f32_e32 v107, v107
	v_add_f32_e32 v37, 1.0, v37
	v_rcp_f32_e32 v36, v36
	v_rcp_f32_e32 v37, v37
	v_pk_mul_f32 v[34:35], v[106:107], v[34:35]
	v_mul_f32_e32 v106, 0xbfb8aa3b, v38
	v_mul_f32_e32 v107, 0xbfb8aa3b, v39
	v_exp_f32_e32 v106, v106
	v_exp_f32_e32 v107, v107
	v_add_f32_e32 v52, 1.0, v52
	v_add_f32_e32 v53, 1.0, v53
	v_add_f32_e32 v106, 1.0, v106
	v_add_f32_e32 v107, 1.0, v107
	v_rcp_f32_e32 v106, v106
	v_rcp_f32_e32 v107, v107
	v_rcp_f32_e32 v52, v52
	v_rcp_f32_e32 v53, v53
	v_pk_mul_f32 v[36:37], v[36:37], v[108:109]
	v_pk_mul_f32 v[108:109], v[40:41], v[120:121]
	v_pk_mul_f32 v[38:39], v[38:39], v[118:119]
	v_mul_f32_e32 v40, 0xbfb8aa3b, v40
	v_mul_f32_e32 v41, 0xbfb8aa3b, v41
	v_pk_mul_f32 v[38:39], v[106:107], v[38:39]
	v_exp_f32_e32 v40, v40
	v_exp_f32_e32 v41, v41
	v_mul_f32_e32 v106, 0xbfb8aa3b, v50
	v_mul_f32_e32 v107, 0xbfb8aa3b, v51
	v_pk_mul_f32 v[50:51], v[50:51], v[102:103]
	v_pk_mul_f32 v[52:53], v[52:53], v[104:105]
	v_mul_f32_e32 v102, 0xbfb8aa3b, v54
	v_mul_f32_e32 v103, 0xbfb8aa3b, v55
	v_pk_mul_f32 v[104:105], v[56:57], v[116:117]
	v_mul_f32_e32 v56, 0xbfb8aa3b, v56
	v_mul_f32_e32 v57, 0xbfb8aa3b, v57
	v_exp_f32_e32 v102, v102
	v_exp_f32_e32 v103, v103
	v_exp_f32_e32 v56, v56
	v_exp_f32_e32 v57, v57
	v_exp_f32_e32 v106, v106
	v_exp_f32_e32 v107, v107
	v_add_f32_e32 v40, 1.0, v40
	v_add_f32_e32 v41, 1.0, v41
	v_rcp_f32_e32 v40, v40
	v_rcp_f32_e32 v41, v41
	v_add_f32_e32 v102, 1.0, v102
	v_add_f32_e32 v103, 1.0, v103
	v_add_f32_e32 v56, 1.0, v56
	v_add_f32_e32 v57, 1.0, v57
	v_rcp_f32_e32 v102, v102
	v_rcp_f32_e32 v103, v103
	v_rcp_f32_e32 v56, v56
	v_rcp_f32_e32 v57, v57
	v_add_f32_e32 v106, 1.0, v106
	v_add_f32_e32 v107, 1.0, v107
	v_rcp_f32_e32 v106, v106
	v_rcp_f32_e32 v107, v107
	v_pk_mul_f32 v[40:41], v[40:41], v[108:109]
	v_pk_mul_f32 v[54:55], v[54:55], v[114:115]
	v_pk_mul_f32 v[108:109], v[2:3], v[238:239] op_sel_hi:[1,0]
	s_waitcnt vmcnt(0)
	v_pk_mul_f32 v[2:3], v[76:77], v[92:93]
	v_pk_mul_f32 v[54:55], v[102:103], v[54:55]
	v_pk_mul_f32 v[56:57], v[56:57], v[104:105]
	v_pk_mul_f32 v[102:103], v[10:11], v[242:243] op_sel_hi:[1,0]
	v_pk_mul_f32 v[104:105], v[4:5], v[238:239] op_sel_hi:[1,0]
	v_pk_mul_f32 v[4:5], v[74:75], v[90:91]
	v_pk_fma_f32 v[10:11], v[84:85], v[88:89], v[2:3]
	v_pk_fma_f32 v[2:3], v[82:83], v[86:87], v[4:5]
	v_pk_fma_f32 v[4:5], v[104:105], v[80:81], v[10:11]
	v_pk_mul_f32 v[10:11], v[84:85], v[92:93]
	v_pk_mul_f32 v[50:51], v[106:107], v[50:51]
	v_pk_mul_f32 v[106:107], v[14:15], v[240:241] op_sel_hi:[1,0]
	v_pk_mul_f32 v[8:9], v[8:9], v[236:237] op_sel_hi:[1,0]
	v_pk_mul_f32 v[14:15], v[82:83], v[90:91]
	v_pk_fma_f32 v[74:75], v[104:105], v[88:89], v[10:11]
	v_pk_mul_f32 v[76:77], v[104:105], v[92:93]
	v_pk_mul_f32 v[12:13], v[12:13], v[242:243] op_sel_hi:[1,0]
	v_pk_fma_f32 v[10:11], v[108:109], v[86:87], v[14:15]
	v_pk_fma_f32 v[14:15], v[8:9], v[80:81], v[74:75]
	v_pk_fma_f32 v[76:77], v[8:9], v[88:89], v[76:77]
	v_pk_mul_f32 v[8:9], v[8:9], v[92:93]
	v_pk_mul_f32 v[6:7], v[6:7], v[236:237] op_sel_hi:[1,0]
	v_pk_fma_f32 v[8:9], v[12:13], v[88:89], v[8:9]
	v_pk_mul_f32 v[74:75], v[108:109], v[90:91]
	v_pk_fma_f32 v[84:85], v[16:17], v[80:81], v[8:9]
	v_pk_mul_f32 v[8:9], v[12:13], v[92:93]
	v_pk_fma_f32 v[10:11], v[6:7], v[78:79], v[10:11]
	v_pk_fma_f32 v[74:75], v[6:7], v[86:87], v[74:75]
	v_pk_mul_f32 v[6:7], v[6:7], v[90:91]
	v_pk_fma_f32 v[8:9], v[16:17], v[88:89], v[8:9]
	v_pk_fma_f32 v[6:7], v[102:103], v[86:87], v[6:7]
	v_pk_fma_f32 v[104:105], v[48:49], v[80:81], v[8:9]
	v_pk_mul_f32 v[8:9], v[16:17], v[92:93]
	v_pk_fma_f32 v[82:83], v[106:107], v[78:79], v[6:7]
	v_pk_mul_f32 v[6:7], v[102:103], v[90:91]
	v_pk_fma_f32 v[8:9], v[48:49], v[88:89], v[8:9]
	v_pk_fma_f32 v[2:3], v[108:109], v[78:79], v[2:3]
	v_pk_fma_f32 v[6:7], v[106:107], v[86:87], v[6:7]
	v_pk_fma_f32 v[108:109], v[44:45], v[80:81], v[8:9]
	v_pk_mul_f32 v[8:9], v[46:47], v[90:91]
	v_pk_fma_f32 v[74:75], v[102:103], v[78:79], v[74:75]
	v_pk_fma_f32 v[102:103], v[46:47], v[78:79], v[6:7]
	v_pk_mul_f32 v[6:7], v[106:107], v[90:91]
	v_pk_fma_f32 v[8:9], v[42:43], v[86:87], v[8:9]
	v_pk_fma_f32 v[6:7], v[46:47], v[86:87], v[6:7]
	v_pk_fma_f32 v[16:17], v[78:79], v[94:95], v[8:9]
	v_pk_mul_f32 v[8:9], v[86:87], v[94:95]
	v_pk_fma_f32 v[106:107], v[42:43], v[78:79], v[6:7]
	v_pk_fma_f32 v[8:9], v[42:43], v[90:91], v[8:9]
	v_mul_f32_e32 v42, 0xbfb8aa3b, v124
	v_mul_f32_e32 v43, 0xbfb8aa3b, v125
	v_exp_f32_e32 v42, v42
	v_exp_f32_e32 v43, v43
	v_pk_mul_f32 v[6:7], v[48:49], v[92:93]
	v_pk_fma_f32 v[76:77], v[12:13], v[80:81], v[76:77]
	v_pk_fma_f32 v[6:7], v[44:45], v[88:89], v[6:7]
	v_add_f32_e32 v42, 1.0, v42
	v_add_f32_e32 v43, 1.0, v43
	v_pk_fma_f32 v[12:13], v[80:81], v[96:97], v[6:7]
	v_pk_mul_f32 v[6:7], v[88:89], v[96:97]
	v_rcp_f32_e32 v42, v42
	v_rcp_f32_e32 v43, v43
	v_pk_fma_f32 v[6:7], v[44:45], v[92:93], v[6:7]
	v_pk_fma_f32 v[8:9], v[78:79], v[98:99], v[8:9]
	v_pk_fma_f32 v[6:7], v[80:81], v[100:101], v[6:7]
	v_pk_mul_f32 v[46:47], v[180:181], v[106:107]
	v_pk_mul_f32 v[44:45], v[122:123], v[6:7]
	v_pk_mul_f32 v[6:7], v[124:125], v[8:9]
	v_mul_f32_e32 v8, 0xbfb8aa3b, v122
	v_mul_f32_e32 v9, 0xbfb8aa3b, v123
	v_pk_mul_f32 v[6:7], v[42:43], v[6:7]
	v_exp_f32_e32 v8, v8
	v_exp_f32_e32 v9, v9
	v_mul_f32_e32 v42, 0xbfb8aa3b, v128
	v_mul_f32_e32 v43, 0xbfb8aa3b, v129
	v_exp_f32_e32 v42, v42
	v_exp_f32_e32 v43, v43
	v_add_f32_e32 v8, 1.0, v8
	v_add_f32_e32 v9, 1.0, v9
	v_rcp_f32_e32 v8, v8
	v_rcp_f32_e32 v9, v9
	v_add_f32_e32 v42, 1.0, v42
	v_add_f32_e32 v43, 1.0, v43
	v_rcp_f32_e32 v42, v42
	v_rcp_f32_e32 v43, v43
	v_pk_mul_f32 v[8:9], v[8:9], v[44:45]
	v_pk_mul_f32 v[44:45], v[126:127], v[12:13]
	v_pk_mul_f32 v[12:13], v[128:129], v[16:17]
	v_mul_f32_e32 v16, 0xbfb8aa3b, v126
	v_pk_mul_f32 v[12:13], v[42:43], v[12:13]
	v_mul_f32_e32 v42, 0xbfb8aa3b, v180
	v_mul_f32_e32 v43, 0xbfb8aa3b, v181
	v_exp_f32_e32 v42, v42
	v_exp_f32_e32 v43, v43
	v_mul_f32_e32 v17, 0xbfb8aa3b, v127
	v_exp_f32_e32 v16, v16
	v_add_f32_e32 v42, 1.0, v42
	v_add_f32_e32 v43, 1.0, v43
	v_rcp_f32_e32 v42, v42
	v_rcp_f32_e32 v43, v43
	v_exp_f32_e32 v17, v17
	v_add_f32_e32 v16, 1.0, v16
	v_pk_mul_f32 v[14:15], v[62:63], v[14:15]
	v_pk_mul_f32 v[42:43], v[42:43], v[46:47]
	v_mul_f32_e32 v46, 0xbfb8aa3b, v178
	v_mul_f32_e32 v47, 0xbfb8aa3b, v179
	v_exp_f32_e32 v46, v46
	v_exp_f32_e32 v47, v47
	v_add_f32_e32 v17, 1.0, v17
	v_mul_f32_e32 v62, 0xbfb8aa3b, v62
	v_mul_f32_e32 v63, 0xbfb8aa3b, v63
	v_rcp_f32_e32 v16, v16
	v_rcp_f32_e32 v17, v17
	v_add_f32_e32 v46, 1.0, v46
	v_add_f32_e32 v47, 1.0, v47
	v_exp_f32_e32 v62, v62
	v_exp_f32_e32 v63, v63
	v_rcp_f32_e32 v46, v46
	v_rcp_f32_e32 v47, v47
	v_pk_mul_f32 v[16:17], v[16:17], v[44:45]
	v_pk_mul_f32 v[44:45], v[178:179], v[108:109]
	v_add_f32_e32 v62, 1.0, v62
	v_add_f32_e32 v63, 1.0, v63
	v_pk_mul_f32 v[44:45], v[46:47], v[44:45]
	v_mul_f32_e32 v46, 0xbfb8aa3b, v156
	v_mul_f32_e32 v47, 0xbfb8aa3b, v157
	v_rcp_f32_e32 v62, v62
	v_rcp_f32_e32 v63, v63
	v_exp_f32_e32 v46, v46
	v_exp_f32_e32 v47, v47
	v_pk_mul_f32 v[78:79], v[156:157], v[102:103]
	v_pk_mul_f32 v[14:15], v[62:63], v[14:15]
	v_mul_f32_e32 v62, 0xbfb8aa3b, v60
	v_mul_f32_e32 v63, 0xbfb8aa3b, v61
	v_add_f32_e32 v46, 1.0, v46
	v_add_f32_e32 v47, 1.0, v47
	v_exp_f32_e32 v62, v62
	v_exp_f32_e32 v63, v63
	v_rcp_f32_e32 v46, v46
	v_rcp_f32_e32 v47, v47
	v_add_f32_e32 v62, 1.0, v62
	v_add_f32_e32 v63, 1.0, v63
	v_rcp_f32_e32 v62, v62
	v_pk_mul_f32 v[46:47], v[46:47], v[78:79]
	v_mul_f32_e32 v78, 0xbfb8aa3b, v154
	v_mul_f32_e32 v79, 0xbfb8aa3b, v155
	v_rcp_f32_e32 v63, v63
	v_exp_f32_e32 v78, v78
	v_exp_f32_e32 v79, v79
	v_pk_mul_f32 v[2:3], v[60:61], v[2:3]
	v_pk_mul_f32 v[48:49], v[154:155], v[104:105]
	v_pk_mul_f32 v[60:61], v[62:63], v[2:3]
	v_mul_f32_e32 v2, 0xbfb8aa3b, v58
	v_mul_f32_e32 v3, 0xbfb8aa3b, v59
	v_add_f32_e32 v78, 1.0, v78
	v_add_f32_e32 v79, 1.0, v79
	v_exp_f32_e32 v2, v2
	v_exp_f32_e32 v3, v3
	v_rcp_f32_e32 v78, v78
	v_rcp_f32_e32 v79, v79
	v_add_f32_e32 v2, 1.0, v2
	v_add_f32_e32 v3, 1.0, v3
	v_rcp_f32_e32 v2, v2
	v_pk_mul_f32 v[48:49], v[78:79], v[48:49]
	v_mul_f32_e32 v78, 0xbfb8aa3b, v72
	v_mul_f32_e32 v79, 0xbfb8aa3b, v73
	v_rcp_f32_e32 v3, v3
	v_exp_f32_e32 v78, v78
	v_exp_f32_e32 v79, v79
	v_pk_mul_f32 v[4:5], v[58:59], v[4:5]
	v_pk_mul_f32 v[80:81], v[70:71], v[84:85]
	v_pk_mul_f32 v[58:59], v[2:3], v[4:5]
	v_cvt_pk_bf16_f32 v4, v6, v7
	v_lshrrev_b32_e32 v130, 2, v213
	v_and_b32_e32 v131, 3, v213
	v_lshlrev_b32_e32 v134, 6, v131
	v_lshl_add_u32 v134, v130, 2, v134
	v_sub_u32_e32 v135, v130, v249
	v_lshl_add_u32 v135, v135, 3, v232
	v_sub_u32_e32 v136, v131, v250
	v_lshl_add_u32 v132, v136, 3, v234
	v_mov_b32_e32 v133, v235
	v_lshlrev_b64 v[132:133], 1, v[132:133]
	v_mov_b64_e32 v[6:7], s[46:47]
	v_add_f32_e32 v78, 1.0, v78
	v_add_f32_e32 v79, 1.0, v79
	v_cvt_pk_bf16_f32 v2, v18, v19
	v_cvt_pk_bf16_f32 v5, v8, v9
	v_mad_i64_i32 v[8:9], s[4:5], v135, s92, v[6:7]
	v_lshlrev_b64 v[18:19], 1, v[234:235]
	v_rcp_f32_e32 v78, v78
	v_rcp_f32_e32 v79, v79
	v_cvt_pk_bf16_f32 v3, v20, v21
	v_lshl_add_u64 v[8:9], v[8:9], 0, v[132:133]
	v_mul_f32_e32 v70, 0xbfb8aa3b, v70
	v_mul_f32_e32 v71, 0xbfb8aa3b, v71
	ds_bpermute_b32 v2, v134, v2
	ds_bpermute_b32 v3, v134, v3
	ds_bpermute_b32 v4, v134, v4
	ds_bpermute_b32 v5, v134, v5
	s_waitcnt lgkmcnt(0)
	global_store_dwordx4 v[8:9], v[2:5], off
	v_or_b32_e32 v8, 1, v135
	v_exp_f32_e32 v70, v70
	v_exp_f32_e32 v71, v71
	v_mad_i64_i32 v[8:9], s[4:5], v8, s92, v[6:7]
	v_pk_mul_f32 v[72:73], v[72:73], v[82:83]
	v_cvt_pk_bf16_f32 v2, v22, v23
	v_cvt_pk_bf16_f32 v3, v24, v25
	v_cvt_pk_bf16_f32 v4, v12, v13
	v_cvt_pk_bf16_f32 v5, v16, v17
	v_lshl_add_u64 v[8:9], v[8:9], 0, v[132:133]
	v_pk_mul_f32 v[72:73], v[78:79], v[72:73]
	v_mul_f32_e32 v78, 0xbfb8aa3b, v68
	v_mul_f32_e32 v79, 0xbfb8aa3b, v69
	v_pk_mul_f32 v[76:77], v[66:67], v[76:77]
	v_mul_f32_e32 v66, 0xbfb8aa3b, v66
	v_mul_f32_e32 v67, 0xbfb8aa3b, v67
	ds_bpermute_b32 v2, v134, v2
	ds_bpermute_b32 v3, v134, v3
	ds_bpermute_b32 v4, v134, v4
	ds_bpermute_b32 v5, v134, v5
	s_waitcnt lgkmcnt(0)
	global_store_dwordx4 v[8:9], v[2:5], off
	v_or_b32_e32 v8, 2, v135
	v_exp_f32_e32 v78, v78
	v_exp_f32_e32 v79, v79
	v_exp_f32_e32 v66, v66
	v_exp_f32_e32 v67, v67
	v_mad_i64_i32 v[8:9], s[4:5], v8, s92, v[6:7]
	v_add_f32_e32 v70, 1.0, v70
	v_add_f32_e32 v71, 1.0, v71
	v_cvt_pk_bf16_f32 v2, v26, v27
	v_cvt_pk_bf16_f32 v3, v28, v29
	v_cvt_pk_bf16_f32 v4, v42, v43
	v_cvt_pk_bf16_f32 v5, v44, v45
	v_lshl_add_u64 v[8:9], v[8:9], 0, v[132:133]
	v_rcp_f32_e32 v70, v70
	v_rcp_f32_e32 v71, v71
	v_pk_mul_f32 v[68:69], v[68:69], v[74:75]
	v_mul_f32_e32 v74, 0xbfb8aa3b, v64
	v_mul_f32_e32 v75, 0xbfb8aa3b, v65
	ds_bpermute_b32 v2, v134, v2
	ds_bpermute_b32 v3, v134, v3
	ds_bpermute_b32 v4, v134, v4
	ds_bpermute_b32 v5, v134, v5
	s_waitcnt lgkmcnt(0)
	global_store_dwordx4 v[8:9], v[2:5], off
	v_or_b32_e32 v8, 3, v135
	v_exp_f32_e32 v74, v74
	v_exp_f32_e32 v75, v75
	v_mad_i64_i32 v[8:9], s[4:5], v8, s92, v[6:7]
	v_add_f32_e32 v78, 1.0, v78
	v_add_f32_e32 v79, 1.0, v79
	v_add_f32_e32 v66, 1.0, v66
	v_add_f32_e32 v67, 1.0, v67
	v_cvt_pk_bf16_f32 v2, v30, v31
	v_cvt_pk_bf16_f32 v3, v32, v33
	v_cvt_pk_bf16_f32 v4, v46, v47
	v_cvt_pk_bf16_f32 v5, v48, v49
	v_lshl_add_u64 v[8:9], v[8:9], 0, v[132:133]
	v_rcp_f32_e32 v78, v78
	v_rcp_f32_e32 v79, v79
	v_rcp_f32_e32 v66, v66
	v_rcp_f32_e32 v67, v67
	ds_bpermute_b32 v2, v134, v2
	ds_bpermute_b32 v3, v134, v3
	ds_bpermute_b32 v4, v134, v4
	ds_bpermute_b32 v5, v134, v5
	s_waitcnt lgkmcnt(0)
	global_store_dwordx4 v[8:9], v[2:5], off
	v_or_b32_e32 v8, 4, v135
	v_pk_mul_f32 v[70:71], v[70:71], v[80:81]
	v_mad_i64_i32 v[8:9], s[4:5], v8, s92, v[6:7]
	v_add_f32_e32 v74, 1.0, v74
	v_add_f32_e32 v75, 1.0, v75
	v_cvt_pk_bf16_f32 v2, v34, v35
	v_cvt_pk_bf16_f32 v3, v36, v37
	v_cvt_pk_bf16_f32 v4, v72, v73
	v_cvt_pk_bf16_f32 v5, v70, v71
	v_lshl_add_u64 v[8:9], v[8:9], 0, v[132:133]
	v_rcp_f32_e32 v74, v74
	v_rcp_f32_e32 v75, v75
	ds_bpermute_b32 v2, v134, v2
	ds_bpermute_b32 v3, v134, v3
	ds_bpermute_b32 v4, v134, v4
	ds_bpermute_b32 v5, v134, v5
	s_waitcnt lgkmcnt(0)
	global_store_dwordx4 v[8:9], v[2:5], off
	v_or_b32_e32 v8, 5, v135
	v_pk_mul_f32 v[68:69], v[78:79], v[68:69]
	v_pk_mul_f32 v[66:67], v[66:67], v[76:77]
	v_mad_i64_i32 v[8:9], s[4:5], v8, s92, v[6:7]
	v_cvt_pk_bf16_f32 v2, v38, v39
	v_cvt_pk_bf16_f32 v3, v40, v41
	v_cvt_pk_bf16_f32 v4, v68, v69
	v_cvt_pk_bf16_f32 v5, v66, v67
	v_lshl_add_u64 v[8:9], v[8:9], 0, v[132:133]
	v_pk_mul_f32 v[10:11], v[64:65], v[10:11]
	ds_bpermute_b32 v2, v134, v2
	ds_bpermute_b32 v3, v134, v3
	ds_bpermute_b32 v4, v134, v4
	ds_bpermute_b32 v5, v134, v5
	s_waitcnt lgkmcnt(0)
	global_store_dwordx4 v[8:9], v[2:5], off
	v_or_b32_e32 v8, 6, v135
	v_pk_mul_f32 v[10:11], v[74:75], v[10:11]
	v_mad_i64_i32 v[8:9], s[4:5], v8, s92, v[6:7]
	v_cvt_pk_bf16_f32 v2, v50, v51
	v_cvt_pk_bf16_f32 v3, v52, v53
	v_cvt_pk_bf16_f32 v4, v10, v11
	v_cvt_pk_bf16_f32 v5, v14, v15
	v_lshl_add_u64 v[8:9], v[8:9], 0, v[132:133]
	ds_bpermute_b32 v2, v134, v2
	ds_bpermute_b32 v3, v134, v3
	ds_bpermute_b32 v4, v134, v4
	ds_bpermute_b32 v5, v134, v5
	s_waitcnt lgkmcnt(0)
	global_store_dwordx4 v[8:9], v[2:5], off
	v_or_b32_e32 v8, 7, v135
	v_mad_i64_i32 v[6:7], s[4:5], v8, s92, v[6:7]
	v_cvt_pk_bf16_f32 v2, v54, v55
	v_cvt_pk_bf16_f32 v3, v56, v57
	v_cvt_pk_bf16_f32 v4, v60, v61
	v_cvt_pk_bf16_f32 v5, v58, v59
	v_lshl_add_u64 v[6:7], v[6:7], 0, v[132:133]
	ds_bpermute_b32 v2, v134, v2
	ds_bpermute_b32 v3, v134, v3
	ds_bpermute_b32 v4, v134, v4
	ds_bpermute_b32 v5, v134, v5
	s_waitcnt lgkmcnt(0)
	global_store_dwordx4 v[6:7], v[2:5], off
	s_andn2_b64 vcc, exec, s[40:41]
	s_cbranch_vccnz .LBB0_386
	s_andn2_b64 vcc, exec, s[24:25]
	s_cbranch_vccnz .LBB0_385
	s_barrier
	s_branch .LBB0_385
